# weight-conversion split moved: 12472 items in the prologue (was 11272), 3400 deferred to the in-projection tail
# speedup vs baseline: 1.0061x; 1.0061x over previous
; #define LAS __attribute__((address_space(3)))
;     __device__ __forceinline__ bf16* Win_t() const { return (bf16*)(ws + WS_WIN); }
;     __device__ __forceinline__ bf16* Wout_t() const { return (bf16*)(ws + WS_WOUT); }
;     __device__ __forceinline__ bf16* Wgu_t() const { return (bf16*)((unsigned char*)out + OUT_WGU); }
; __device__ __forceinline__ P0Item p0_decode(Frame& F, int it, int n4) {
;     constexpr int I_IN = (D / 64) * (NP1 / 64), I_OUT = (D / 64) * (D / 64), I_GU = (D / 64) * (2 * FF / 64);
;     P0Item q; int r = it;
;     if (r < I_IN) { const int nblk = NP1 / 64, kb = r / nblk, nb = r % nblk, n = nb * 64 + n4;
;         const int sc = n < SRC_GLR ? n : n + GRANK;
;         q.srcp = F.w_in + sc; q.ldw = DIN; q.kscale = F.norm1_w; q.K = D; q.WT = F.Win_t(); q.n0 = nb * 64; q.k0 = kb * 64; return q; }
;     r -= I_IN;
;     if (r < I_OUT) { const int nblk = D / 64, kb = r / nblk, nb = r % nblk;
;         q.srcp = F.w_out + nb * 64 + n4; q.ldw = D; q.kscale = nullptr; q.K = D; q.WT = F.Wout_t(); q.n0 = nb * 64; q.k0 = kb * 64; return q; }
;     r -= I_OUT;
;     if (r < I_GU) { const int nblk = 2 * FF / 64, kb = r / nblk, nb = r % nblk, n0 = nb * 64, pn = n0 >> 8, wc = (n0 >> 6) & 3, bj = n4 >> 5, hl = 32 * wc + (n4 & 31);
;         q.srcp = (bj ? F.w_up : F.w_gate) + pn * 128 + hl; q.ldw = FF; q.kscale = F.norm2_w; q.K = D; q.WT = F.Wgu_t(); q.n0 = n0; q.k0 = kb * 64; return q; }
; template <bool NT> __device__ __forceinline__ void p0_items(Frame& F, int it0, int it1, int gw, int nw) {
;     LAS unsigned char* scr = F.lds + F.wave * 16384;
;     const int n4 = (F.lane & 15) * 4, kr = F.lane >> 4;
;     f32x4 va[16], vb[16]; P0Item A, B; int it = it0 + gw;
;     if (it < it1) { A = p0_decode(F, it, n4); p0_load(A, kr, va); }
.LBB0_16:
	s_add_u32 s4, s54, 0x4000000
	s_addc_u32 s5, s55, 0
	v_lshlrev_b32_e32 v2, 2, v183
	s_add_u32 s6, s56, 0xa00000
	v_and_b32_e32 v141, 60, v2
	s_addc_u32 s7, s57, 0
	s_add_u32 s18, s56, 0x2800000
	v_and_b32_e32 v142, 28, v2
	v_mov_b32_e32 v2, s93
	v_mov_b32_e32 v3, s91
	v_cmp_gt_u32_e32 vcc, 32, v141
	v_lshrrev_b32_e32 v1, 4, v183
	s_addc_u32 s19, s57, 0
	v_cndmask_b32_e32 v135, v2, v3, vcc
	v_mov_b32_e32 v2, s92
	v_mov_b32_e32 v3, s90
	s_cmpk_gt_i32 s16, 0x30b7
	v_cndmask_b32_e32 v134, v2, v3, vcc
	v_or_b32_e32 v143, 4, v1
	v_or_b32_e32 v145, 8, v1
	v_or_b32_e32 v146, 12, v1
	v_or_b32_e32 v147, 16, v1
	v_or_b32_e32 v148, 20, v1
	v_or_b32_e32 v149, 24, v1
	v_or_b32_e32 v150, 28, v1
	v_or_b32_e32 v151, 32, v1
	v_or_b32_e32 v152, 36, v1
	v_or_b32_e32 v153, 40, v1
	v_or_b32_e32 v154, 44, v1
	v_or_b32_e32 v155, 48, v1
	v_or_b32_e32 v156, 52, v1
	v_or_b32_e32 v157, 56, v1
	v_or_b32_e32 v158, 60, v1
	s_cbranch_scc1 .LBB0_19
	s_mul_hi_i32 s1, s16, 0x51eb851f
	s_lshr_b32 s8, s1, 31
	s_ashr_i32 s1, s1, 6
	s_add_i32 s1, s1, s8
	s_mul_i32 s8, s1, 0xc8
	s_sub_i32 s8, s16, s8
	s_lshl_b32 s17, s8, 6
	v_or_b32_e32 v2, s17, v141
	s_movk_i32 s8, 0x1a00
	s_cmpk_lt_i32 s16, 0x1900
	v_cmp_gt_i32_e32 vcc, s8, v2
	s_cbranch_scc1 .LBB0_20
	s_cmpk_lt_u32 s16, 0x1d00
	s_cselect_b64 vcc, -1, 0
	s_add_i32 s1, s16, 0xe300
	s_and_b32 s8, s1, 0xffff
	s_mul_i32 s8, s8, 0xba2f
	s_lshr_b32 s8, s8, 23
	s_mul_i32 s9, s8, 0xb0
	s_sub_i32 s1, s1, s9
	s_and_b32 s1, s1, 0xffff
	s_lshl_b32 s10, s1, 5
	s_and_b32 s10, s10, 0x60
	s_lshl_b32 s9, s1, 6
	v_or_b32_e32 v4, s10, v142
	s_lshl_b32 s1, s1, 7
	s_and_b32 s10, s0, 0x7c0
	s_and_b32 s20, s1, 0x7e00
	s_mov_b32 s21, 0
	s_lshl_b32 s8, s8, 6
	s_lshl_b32 s0, s10, 2
	v_lshl_add_u64 v[2:3], v[134:135], 0, s[20:21]
	v_lshlrev_b32_e32 v4, 2, v4
	v_mov_b32_e32 v5, 0
	s_add_u32 s0, s50, s0
	v_lshl_add_u64 v[2:3], v[2:3], 0, v[4:5]
	s_addc_u32 s1, s51, 0
	v_lshlrev_b32_e32 v4, 2, v141
	v_lshl_add_u64 v[4:5], s[0:1], 0, v[4:5]
	s_lshl_b32 s0, s16, 1
	s_and_b32 s0, s0, 0x3fc0
	s_add_i32 s11, s0, 0xffffce00
	s_and_b64 s[0:1], vcc, exec
	s_movk_i32 s0, 0x800
	v_cndmask_b32_e32 v27, v3, v5, vcc
	v_cndmask_b32_e32 v26, v2, v4, vcc
	s_cselect_b32 s23, 0, s89
	s_cselect_b32 s22, 0, s88
	s_cselect_b32 s25, s7, s5
	s_cselect_b32 s24, s6, s4
	s_cselect_b32 s20, s0, 0x1600
	s_cselect_b32 s17, s10, s9
	s_cselect_b32 s63, s11, s8
	s_branch .LBB0_21

;     __device__ __forceinline__ bf16* Win_t() const { return (bf16*)(ws + WS_WIN); }
;     __device__ __forceinline__ bf16* Wout_t() const { return (bf16*)(ws + WS_WOUT); }
;     __device__ __forceinline__ bf16* Wgu_t() const { return (bf16*)((unsigned char*)out + OUT_WGU); }
; __device__ __forceinline__ P0Item p0_decode(Frame& F, int it, int n4) {
;     ...
;     if (r < I_IN) { const int nblk = NP1 / 64, kb = r / nblk, nb = r % nblk, n = nb * 64 + n4;
;         const int sc = n < SRC_GLR ? n : n + GRANK;
;         q.srcp = F.w_in + sc; q.ldw = DIN; q.kscale = F.norm1_w; q.K = D; q.WT = F.Win_t(); q.n0 = nb * 64; q.k0 = kb * 64; return q; }
;     r -= I_IN;
;     if (r < I_OUT) { const int nblk = D / 64, kb = r / nblk, nb = r % nblk;
;         q.srcp = F.w_out + nb * 64 + n4; q.ldw = D; q.kscale = nullptr; q.K = D; q.WT = F.Wout_t(); q.n0 = nb * 64; q.k0 = kb * 64; return q; }
;     r -= I_OUT;
;     if (r < I_GU) { const int nblk = 2 * FF / 64, kb = r / nblk, nb = r % nblk, n0 = nb * 64, pn = n0 >> 8, wc = (n0 >> 6) & 3, bj = n4 >> 5, hl = 32 * wc + (n4 & 31);
;         q.srcp = (bj ? F.w_up : F.w_gate) + pn * 128 + hl; q.ldw = FF; q.kscale = F.norm2_w; q.K = D; q.WT = F.Wgu_t(); q.n0 = n0; q.k0 = kb * 64; return q; }
; template <bool NT> __device__ __forceinline__ void p0_items(Frame& F, int it0, int it1, int gw, int nw) {
;     ...
;     while (it < it1) {
;         int itn = it + nw;
;         if (itn < it1) { B = p0_decode(F, itn, n4); p0_load(B, kr, vb); }
;         p0_finish<NT>(A, va, scr, F.lane);
;         it = itn; if (it >= it1) break;
;         itn = it + nw;
;         if (itn < it1) { A = p0_decode(F, itn, n4); p0_load(A, kr, va); }
.LBB0_57:
	s_cmpk_gt_i32 s65, 0x30b7
	s_mov_b64 s[34:35], -1
	s_cbranch_scc1 .LBB0_56
	s_add_i32 s65, s65, s20
	s_cmpk_lt_i32 s65, 0x30b8
	s_cselect_b64 s[68:69], -1, 0
	s_cmpk_gt_i32 s65, 0x30b7
	s_cselect_b64 s[34:35], -1, 0
	s_and_b64 vcc, exec, s[34:35]
	s_cbranch_vccnz .LBB0_100
	s_cmpk_gt_i32 s65, 0x18ff
	s_cbranch_scc0 .LBB0_62
	s_cmpk_gt_u32 s65, 0x1cff
	s_cbranch_scc0 .LBB0_63
	s_add_i32 s0, s65, 0xe300
	s_and_b32 s1, s0, 0xffff
	s_mul_i32 s1, s1, 0xba2f
	s_lshr_b32 s1, s1, 23
	s_mul_i32 s8, s1, 0xb0
	s_sub_i32 s0, s0, s8
	s_and_b32 s0, s0, 0xffff
	s_lshl_b32 s8, s0, 5
	s_lshl_b32 s67, s0, 6
	s_and_b32 s8, s8, 0x60
	s_lshl_b32 s0, s0, 7
	v_or_b32_e32 v27, s8, v142
	s_and_b32 s26, s0, 0x7e00
	v_lshl_add_u64 v[28:29], v[134:135], 0, s[26:27]
	v_lshlrev_b32_e32 v46, 2, v27
	v_mov_b32_e32 v47, v26
	v_lshl_add_u64 v[138:139], v[28:29], 0, v[46:47]
	s_lshl_b32 s74, s1, 6
	s_mov_b64 s[28:29], s[88:89]
	s_mov_b64 s[70:71], 0x1600
	s_mov_b64 s[30:31], s[4:5]
	s_cbranch_execz .LBB0_64
	s_branch .LBB0_65

; #define GAS __attribute__((address_space(1)))
; #define LAS __attribute__((address_space(3)))
; __device__ __forceinline__ s16x4_t tr_read(LAS const unsigned char* p) { return __builtin_bit_cast(s16x4_t, __builtin_amdgcn_ds_read_tr16_b64_v4i16((LAS s16x4_t*)p)); }
; __device__ __forceinline__ bf16x8_t cat8(s16x4_t lo, s16x4_t hi) { return __builtin_shufflevector(lo, hi, 0, 1, 2, 3, 4, 5, 6, 7); }
; template <bool NT> __device__ __forceinline__ void p0_finish(const P0Item& q, f32x4 (&v)[16], LAS unsigned char* scr, int lane) {
;     ...
;         for (int i = 0; i < 16; ++i) v[i] = v[i] * q.kscale[q.k0 + 4 * i + kr];
;     }
; #pragma unroll
;     for (int i = 0; i < 16; ++i) { v2u w; w.x = cvtpk(v[i][0], v[i][1]); w.y = cvtpk(v[i][2], v[i][3]); *(LAS v2u*)(scr + (4 * i + kr) * RS + n4 * 2) = w; }
;     const int G = lane >> 4, i16 = lane & 15, qq = i16 >> 2, p = i16 & 3;
; #pragma unroll
;     for (int ng = 0; ng < 4; ++ng)
; #pragma unroll
;         for (int u = 0; u < 2; ++u) { const LAS unsigned char* rp = scr + (8 * (G + 4 * u) + qq) * RS + (16 * ng + 4 * p) * 2;
;             const bf16x8_t t = cat8(tr_read(rp), tr_read(rp + 4 * RS));
;             *(GAS bf16x8_t*)(q.WT + pg8::blk_off_b(q.n0 + 16 * ng + i16, q.k0 + 8 * (G + 4 * u), q.K)) = t; }
.LBB0_102:
	s_waitcnt vmcnt(0)
	v_cvt_pk_bf16_f32 v28, v2, v3
	v_cvt_pk_bf16_f32 v29, v4, v5
	v_cvt_pk_bf16_f32 v138, v6, v7
	v_cvt_pk_bf16_f32 v139, v8, v9
	ds_write2_b64 v165, v[28:29], v[138:139] offset1:72
	v_cvt_pk_bf16_f32 v28, v10, v11
	v_cvt_pk_bf16_f32 v29, v12, v13
	v_cvt_pk_bf16_f32 v138, v14, v15
	v_cvt_pk_bf16_f32 v139, v16, v17
	ds_write2_b64 v165, v[28:29], v[138:139] offset0:144 offset1:216
	v_cvt_pk_bf16_f32 v28, v18, v19
	v_cvt_pk_bf16_f32 v29, v20, v21
	v_cvt_pk_bf16_f32 v138, v22, v23
	v_cvt_pk_bf16_f32 v139, v24, v25
	v_add_u32_e32 v168, 0x800, v165
	ds_write2_b64 v168, v[28:29], v[138:139] offset0:32 offset1:104
	v_cvt_pk_bf16_f32 v28, v30, v31
	v_cvt_pk_bf16_f32 v29, v32, v33
	v_cvt_pk_bf16_f32 v138, v34, v35
	v_cvt_pk_bf16_f32 v139, v36, v37
	ds_write2_b64 v168, v[28:29], v[138:139] offset0:176 offset1:248
	v_cvt_pk_bf16_f32 v28, v38, v39
	v_cvt_pk_bf16_f32 v29, v40, v41
	v_cvt_pk_bf16_f32 v138, v42, v43
	v_cvt_pk_bf16_f32 v139, v44, v45
	v_add_u32_e32 v169, 0x1000, v165
	ds_write2_b64 v169, v[28:29], v[138:139] offset0:64 offset1:136
	v_cvt_pk_bf16_f32 v28, v50, v51
	v_cvt_pk_bf16_f32 v29, v52, v53
	v_cvt_pk_bf16_f32 v138, v58, v59
	v_cvt_pk_bf16_f32 v139, v60, v61
	v_add_u32_e32 v170, 0x1400, v165
	ds_write2_b64 v170, v[28:29], v[138:139] offset0:80 offset1:152
	v_cvt_pk_bf16_f32 v28, v74, v75
	v_cvt_pk_bf16_f32 v29, v76, v77
	v_cvt_pk_bf16_f32 v138, v82, v83
	v_cvt_pk_bf16_f32 v139, v84, v85
	v_add_u32_e32 v171, 0x1800, v165
	ds_write2_b64 v171, v[28:29], v[138:139] offset0:96 offset1:168
	v_cvt_pk_bf16_f32 v28, v94, v95
	v_cvt_pk_bf16_f32 v29, v96, v97
	v_cvt_pk_bf16_f32 v138, v102, v103
	v_cvt_pk_bf16_f32 v139, v104, v105
	v_add_u32_e32 v172, 0x1c00, v165
	v_add_u32_e32 v27, s17, v140
	ds_write2_b64 v172, v[28:29], v[138:139] offset0:112 offset1:184
	v_lshlrev_b32_e32 v28, 2, v27
	v_and_b32_e32 v28, 16, v28
	v_lshrrev_b32_e32 v29, 1, v27
	v_add_u32_e32 v138, s63, v160
	v_and_or_b32 v173, v29, s21, v28
	v_ashrrev_i32_e32 v28, 3, v27
	v_and_b32_e32 v139, 3, v27
	v_and_b32_e32 v182, 0xffffffe0, v28
	v_ashrrev_i32_e32 v204, 6, v138
	v_and_or_b32 v139, v29, 12, v139
	v_add_u32_e32 v28, v182, v204
	ds_read_b64_tr_b16 v[176:177], v166 offset:576
	v_ashrrev_i32_e32 v29, 31, v28
	v_lshlrev_b32_e32 v192, 5, v139
	v_and_b32_e32 v206, 31, v138
	v_and_b32_e32 v193, 16, v27
	v_lshrrev_b32_e32 v173, 3, v173
	v_bfe_u32 v205, v138, 5, 1
	v_bitop3_b32 v175, v192, v193, v206 bitop3:0x36
	v_lshlrev_b64 v[28:29], 15, v[28:29]
	v_lshlrev_b32_e32 v27, 9, v27
	v_or_b32_e32 v174, v173, v205
	v_lshl_add_u64 v[28:29], s[24:25], 0, v[28:29]
	v_and_b32_e32 v138, 0x4000, v27
	v_mov_b32_e32 v139, v26
	v_lshlrev_b32_e32 v27, 1, v175
	v_lshl_add_u64 v[28:29], v[28:29], 0, v[138:139]
	v_lshl_or_b32 v174, v174, 10, v27
	v_mov_b32_e32 v175, v26
	v_add_u32_e32 v27, s63, v161
	v_lshl_add_u64 v[28:29], v[28:29], 0, v[174:175]
	v_ashrrev_i32_e32 v207, 6, v27
	ds_read_b64_tr_b16 v[174:175], v166
	ds_read_b64_tr_b16 v[178:179], v166 offset:32
	ds_read_b64_tr_b16 v[184:185], v166 offset:64
	ds_read_b64_tr_b16 v[188:189], v166 offset:96
	ds_read_b64_tr_b16 v[180:181], v166 offset:608
	ds_read_b64_tr_b16 v[186:187], v166 offset:640
	ds_read_b64_tr_b16 v[190:191], v166 offset:672
	s_waitcnt lgkmcnt(6)
	global_store_dwordx4 v[28:29], v[174:177], off
	v_add_u32_e32 v28, v182, v207
	v_ashrrev_i32_e32 v29, 31, v28
	ds_read_b64_tr_b16 v[176:177], v167 offset:576
	v_bfe_u32 v182, v27, 5, 1
	v_and_b32_e32 v27, 31, v27
	v_lshlrev_b64 v[28:29], 15, v[28:29]
	v_bitop3_b32 v174, v192, v193, v27 bitop3:0x36
	v_lshl_add_u64 v[28:29], s[24:25], 0, v[28:29]
	v_or_b32_e32 v173, v173, v182
	v_lshl_add_u64 v[28:29], v[28:29], 0, v[138:139]
	v_lshlrev_b32_e32 v138, 1, v174
	v_lshl_or_b32 v138, v173, 10, v138
	v_lshl_add_u64 v[28:29], v[28:29], 0, v[138:139]
	v_add_u32_e32 v138, s17, v162
	ds_read_b64_tr_b16 v[174:175], v167
	ds_read_b64_tr_b16 v[192:193], v167 offset:32
	ds_read_b64_tr_b16 v[196:197], v167 offset:64
	ds_read_b64_tr_b16 v[200:201], v167 offset:96
	ds_read_b64_tr_b16 v[194:195], v167 offset:608
	ds_read_b64_tr_b16 v[198:199], v167 offset:640
	ds_read_b64_tr_b16 v[202:203], v167 offset:672
	s_waitcnt lgkmcnt(6)
; #define GAS __attribute__((address_space(1)))
; #define LAS __attribute__((address_space(3)))
; #define LDS_WAIT() asm volatile("s_waitcnt lgkmcnt(0)" ::: "memory")
; __device__ __forceinline__ s16x4_t tr_read(LAS const unsigned char* p) { return __builtin_bit_cast(s16x4_t, __builtin_amdgcn_ds_read_tr16_b64_v4i16((LAS s16x4_t*)p)); }
; __device__ __forceinline__ bf16x8_t cat8(s16x4_t lo, s16x4_t hi) { return __builtin_shufflevector(lo, hi, 0, 1, 2, 3, 4, 5, 6, 7); }
; template <bool NT> __device__ __forceinline__ void p0_finish(const P0Item& q, f32x4 (&v)[16], LAS unsigned char* scr, int lane) {
;     ...
;         for (int u = 0; u < 2; ++u) { const LAS unsigned char* rp = scr + (8 * (G + 4 * u) + qq) * RS + (16 * ng + 4 * p) * 2;
;             const bf16x8_t t = cat8(tr_read(rp), tr_read(rp + 4 * RS));
;             *(GAS bf16x8_t*)(q.WT + pg8::blk_off_b(q.n0 + 16 * ng + i16, q.k0 + 8 * (G + 4 * u), q.K)) = t; }
;     LDS_WAIT(); asm volatile("" ::: "memory");
; }
; template <bool NT> __device__ __forceinline__ void p0_items(Frame& F, int it0, int it1, int gw, int nw) {
;     LAS unsigned char* scr = F.lds + F.wave * 16384;
;     const int n4 = (F.lane & 15) * 4, kr = F.lane >> 4;
;     f32x4 va[16], vb[16]; P0Item A, B; int it = it0 + gw;
;     if (it < it1) { A = p0_decode(F, it, n4); p0_load(A, kr, va); }
;     while (it < it1) {
;         int itn = it + nw;
;         if (itn < it1) { B = p0_decode(F, itn, n4); p0_load(B, kr, vb); }
;         p0_finish<NT>(A, va, scr, F.lane);
;         it = itn; if (it >= it1) break;
;         itn = it + nw;
;         if (itn < it1) { A = p0_decode(F, itn, n4); p0_load(A, kr, va); }
;         p0_finish<NT>(B, vb, scr, F.lane);
;         it = itn;
	global_store_dwordx4 v[28:29], v[174:177], off
	v_lshlrev_b32_e32 v28, 2, v138
	v_and_b32_e32 v28, 16, v28
	v_lshrrev_b32_e32 v29, 1, v138
	v_and_or_b32 v173, v29, s21, v28
	v_ashrrev_i32_e32 v28, 3, v138
	v_and_b32_e32 v139, 3, v138
	v_and_b32_e32 v176, 0xffffffe0, v28
	v_and_or_b32 v139, v29, 12, v139
	v_add_u32_e32 v28, v176, v204
	v_ashrrev_i32_e32 v29, 31, v28
	v_lshlrev_b32_e32 v177, 5, v139
	v_and_b32_e32 v208, 16, v138
	v_lshrrev_b32_e32 v173, 3, v173
	v_bitop3_b32 v175, v177, v208, v206 bitop3:0x36
	v_lshlrev_b64 v[28:29], 15, v[28:29]
	v_lshlrev_b32_e32 v138, 9, v138
	v_or_b32_e32 v174, v173, v205
	v_lshl_add_u64 v[28:29], s[24:25], 0, v[28:29]
	v_and_b32_e32 v138, 0x4000, v138
	v_mov_b32_e32 v139, v26
	v_lshlrev_b32_e32 v175, 1, v175
	v_lshl_add_u64 v[28:29], v[28:29], 0, v[138:139]
	v_lshl_or_b32 v174, v174, 10, v175
	v_mov_b32_e32 v175, v26
	v_lshl_add_u64 v[28:29], v[28:29], 0, v[174:175]
	global_store_dwordx4 v[28:29], v[178:181], off
	v_add_u32_e32 v28, v176, v207
	v_ashrrev_i32_e32 v29, 31, v28
	v_lshlrev_b64 v[28:29], 15, v[28:29]
	v_bitop3_b32 v174, v177, v208, v27 bitop3:0x36
	v_lshl_add_u64 v[28:29], s[24:25], 0, v[28:29]
	v_or_b32_e32 v173, v173, v182
	v_lshl_add_u64 v[28:29], v[28:29], 0, v[138:139]
	v_lshlrev_b32_e32 v138, 1, v174
	v_lshl_or_b32 v138, v173, 10, v138
	v_lshl_add_u64 v[28:29], v[28:29], 0, v[138:139]
	v_add_u32_e32 v138, s17, v163
	s_waitcnt lgkmcnt(2)
	global_store_dwordx4 v[28:29], v[192:195], off
	v_lshlrev_b32_e32 v28, 2, v138
	v_and_b32_e32 v28, 16, v28
	v_lshrrev_b32_e32 v29, 1, v138
	v_and_or_b32 v173, v29, s21, v28
	v_ashrrev_i32_e32 v28, 3, v138
	v_and_b32_e32 v139, 3, v138
	v_and_b32_e32 v176, 0xffffffe0, v28
	v_and_or_b32 v139, v29, 12, v139
	v_add_u32_e32 v28, v176, v204
	v_ashrrev_i32_e32 v29, 31, v28
	v_lshlrev_b32_e32 v177, 5, v139
	v_and_b32_e32 v178, 16, v138
	v_lshrrev_b32_e32 v173, 3, v173
	v_bitop3_b32 v175, v177, v178, v206 bitop3:0x36
	v_lshlrev_b64 v[28:29], 15, v[28:29]
	v_lshlrev_b32_e32 v138, 9, v138
	v_or_b32_e32 v174, v173, v205
	v_lshl_add_u64 v[28:29], s[24:25], 0, v[28:29]
	v_and_b32_e32 v138, 0x4000, v138
	v_mov_b32_e32 v139, v26
	v_lshlrev_b32_e32 v175, 1, v175
	v_lshl_add_u64 v[28:29], v[28:29], 0, v[138:139]
	v_lshl_or_b32 v174, v174, 10, v175
	v_mov_b32_e32 v175, v26
	v_lshl_add_u64 v[28:29], v[28:29], 0, v[174:175]
	global_store_dwordx4 v[28:29], v[184:187], off
	v_add_u32_e32 v28, v176, v207
	v_ashrrev_i32_e32 v29, 31, v28
	v_lshlrev_b64 v[28:29], 15, v[28:29]
	v_bitop3_b32 v174, v177, v178, v27 bitop3:0x36
	v_lshl_add_u64 v[28:29], s[24:25], 0, v[28:29]
	v_or_b32_e32 v173, v173, v182
	v_lshl_add_u64 v[28:29], v[28:29], 0, v[138:139]
	v_lshlrev_b32_e32 v138, 1, v174
	v_lshl_or_b32 v138, v173, 10, v138
	v_lshl_add_u64 v[28:29], v[28:29], 0, v[138:139]
	v_add_u32_e32 v138, s17, v164
	s_waitcnt lgkmcnt(1)
	global_store_dwordx4 v[28:29], v[196:199], off
	v_lshlrev_b32_e32 v28, 2, v138
	v_and_b32_e32 v28, 16, v28
	v_lshrrev_b32_e32 v29, 1, v138
	v_and_or_b32 v173, v29, s21, v28
	v_ashrrev_i32_e32 v28, 3, v138
	v_and_b32_e32 v139, 3, v138
	v_and_b32_e32 v176, 0xffffffe0, v28
	v_and_or_b32 v139, v29, 12, v139
	v_add_u32_e32 v28, v176, v204
	v_ashrrev_i32_e32 v29, 31, v28
	v_lshlrev_b32_e32 v177, 5, v139
	v_and_b32_e32 v178, 16, v138
	v_lshrrev_b32_e32 v173, 3, v173
	v_bitop3_b32 v175, v177, v178, v206 bitop3:0x36
	v_lshlrev_b64 v[28:29], 15, v[28:29]
	v_lshlrev_b32_e32 v138, 9, v138
	v_or_b32_e32 v174, v173, v205
	v_lshl_add_u64 v[28:29], s[24:25], 0, v[28:29]
	v_and_b32_e32 v138, 0x4000, v138
	v_mov_b32_e32 v139, v26
	v_lshlrev_b32_e32 v175, 1, v175
	v_lshl_add_u64 v[28:29], v[28:29], 0, v[138:139]
	v_lshl_or_b32 v174, v174, 10, v175
	v_mov_b32_e32 v175, v26
	v_lshl_add_u64 v[28:29], v[28:29], 0, v[174:175]
	global_store_dwordx4 v[28:29], v[188:191], off
	v_add_u32_e32 v28, v176, v207
	v_ashrrev_i32_e32 v29, 31, v28
	v_bitop3_b32 v27, v177, v178, v27 bitop3:0x36
	v_lshlrev_b64 v[28:29], 15, v[28:29]
	v_or_b32_e32 v173, v173, v182
	v_lshl_add_u64 v[28:29], s[24:25], 0, v[28:29]
	v_lshlrev_b32_e32 v27, 1, v27
	v_lshl_add_u64 v[28:29], v[28:29], 0, v[138:139]
	v_lshl_or_b32 v138, v173, 10, v27
	v_lshl_add_u64 v[28:29], v[28:29], 0, v[138:139]
	s_waitcnt lgkmcnt(0)
	global_store_dwordx4 v[28:29], v[200:203], off
	s_waitcnt lgkmcnt(0)
	s_andn2_b64 vcc, exec, s[68:69]
	s_cbranch_vccnz .LBB0_56
	s_add_i32 s65, s65, s20
	s_cmpk_gt_i32 s65, 0x30b7
	s_cbranch_scc1 .LBB0_145
	s_cmpk_gt_i32 s65, 0x18ff
	s_cbranch_scc0 .LBB0_107
	s_cmpk_gt_u32 s65, 0x1cff
	s_cbranch_scc0 .LBB0_108
	s_add_i32 s0, s65, 0xe300
	s_and_b32 s1, s0, 0xffff
	s_mul_i32 s1, s1, 0xba2f
	s_lshr_b32 s1, s1, 23
	s_mul_i32 s8, s1, 0xb0
	s_sub_i32 s0, s0, s8
	s_and_b32 s0, s0, 0xffff
	s_lshl_b32 s8, s0, 5
	s_lshl_b32 s17, s0, 6
	s_and_b32 s8, s8, 0x60
	s_lshl_b32 s0, s0, 7
	v_or_b32_e32 v4, s8, v142
	s_and_b32 s26, s0, 0x7e00
	v_lshl_add_u64 v[2:3], v[134:135], 0, s[26:27]
	v_lshlrev_b32_e32 v4, 2, v4
	v_mov_b32_e32 v5, v26
	v_lshl_add_u64 v[138:139], v[2:3], 0, v[4:5]
	s_lshl_b32 s63, s1, 6
	s_mov_b64 s[22:23], s[88:89]
	s_mov_b64 s[68:69], 0x1600
	s_mov_b64 s[24:25], s[4:5]
	s_cbranch_execz .LBB0_109
	s_branch .LBB0_110

;     __device__ __forceinline__ bf16* Win_t() const { return (bf16*)(ws + WS_WIN); }
;     __device__ __forceinline__ bf16* Wout_t() const { return (bf16*)(ws + WS_WOUT); }
;     __device__ __forceinline__ bf16* Wdown_t() const { return (bf16*)(ws + WS_WDOWN); }
;     __device__ __forceinline__ bf16* Wgu_t() const { return (bf16*)((unsigned char*)out + OUT_WGU); }
; __device__ __forceinline__ P0Item p0_decode(Frame& F, int it, int n4) {
;     ...
;     if (r < I_IN) { const int nblk = NP1 / 64, kb = r / nblk, nb = r % nblk, n = nb * 64 + n4;
;         const int sc = n < SRC_GLR ? n : n + GRANK;
;         q.srcp = F.w_in + sc; q.ldw = DIN; q.kscale = F.norm1_w; q.K = D; q.WT = F.Win_t(); q.n0 = nb * 64; q.k0 = kb * 64; return q; }
;     r -= I_IN;
;     if (r < I_OUT) { const int nblk = D / 64, kb = r / nblk, nb = r % nblk;
;         q.srcp = F.w_out + nb * 64 + n4; q.ldw = D; q.kscale = nullptr; q.K = D; q.WT = F.Wout_t(); q.n0 = nb * 64; q.k0 = kb * 64; return q; }
;     r -= I_OUT;
;     if (r < I_GU) { const int nblk = 2 * FF / 64, kb = r / nblk, nb = r % nblk, n0 = nb * 64, pn = n0 >> 8, wc = (n0 >> 6) & 3, bj = n4 >> 5, hl = 32 * wc + (n4 & 31);
;         q.srcp = (bj ? F.w_up : F.w_gate) + pn * 128 + hl; q.ldw = FF; q.kscale = F.norm2_w; q.K = D; q.WT = F.Wgu_t(); q.n0 = n0; q.k0 = kb * 64; return q; }
;     r -= I_GU;
;     { const int nblk = D / 64, kb = r / nblk, nb = r % nblk;
;         q.srcp = F.w_down + nb * 64 + n4; q.ldw = D; q.kscale = nullptr; q.K = FF; q.WT = F.Wdown_t(); q.n0 = nb * 64; q.k0 = kb * 64; return q; }
; __global__ void __launch_bounds__(NTHREADS, 2) hybrid_fwd(Args args) {
;     ...
;                 p1_glr(F, sw, nshort * NWAVES); p0_items<true>(F, P0_NITEMS - P0_DEFER_ITEMS, P0_NITEMS, sw, nshort * NWAVES); }
;             else if ((NT % F.G) == 0) { p1_glr(F, F.vcu * NWAVES + F.wave, F.G * NWAVES); p0_items<true>(F, P0_NITEMS - P0_DEFER_ITEMS, P0_NITEMS, F.vcu * NWAVES + F.wave, F.G * NWAVES); }
.LBB0_228:
	v_lshlrev_b32_e32 v20, 2, v183
	s_add_i32 s67, s0, 0x30b8
	v_and_b32_e32 v142, 60, v20
	s_cmpk_gt_i32 s0, 0x11f7
	v_lshrrev_b32_e32 v143, 4, v183
	s_cbranch_scc1 .LBB0_233
	s_cmpk_gt_i32 s0, 0xecf7
	s_cbranch_scc0 .LBB0_234
	s_cmpk_gt_u32 s67, 0x1cff
	s_cbranch_scc0 .LBB0_235
	s_cmpk_gt_u32 s67, 0x32ff
	s_cbranch_scc0 .LBB0_236
	s_lshl_b32 s0, s67, 6
	s_and_b32 s64, s0, 0x7c0
	s_lshl_b32 s0, s64, 2
	s_add_u32 s0, s94, s0
	s_addc_u32 s1, s95, 0
	v_lshlrev_b32_e32 v2, 2, v142
	v_mov_b32_e32 v3, 0
	s_add_u32 s18, s56, 0x1200000
	v_lshl_add_u64 v[18:19], s[0:1], 0, v[2:3]
	s_addc_u32 s19, s57, 0
	s_lshl_b32 s0, s67, 1
	s_and_b32 s0, s0, 0x7fffffc0
	s_add_i32 s65, s0, 0xffff9a00
	s_mov_b64 s[20:21], 0
	s_mov_b64 s[6:7], 0
	s_branch .LBB0_237

;     __device__ __forceinline__ bf16* Win_t() const { return (bf16*)(ws + WS_WIN); }
;     __device__ __forceinline__ bf16* Wout_t() const { return (bf16*)(ws + WS_WOUT); }
;     __device__ __forceinline__ bf16* Wdown_t() const { return (bf16*)(ws + WS_WDOWN); }
;     __device__ __forceinline__ bf16* Wgu_t() const { return (bf16*)((unsigned char*)out + OUT_WGU); }
; __device__ __forceinline__ P0Item p0_decode(Frame& F, int it, int n4) {
;     ...
;     if (r < I_IN) { const int nblk = NP1 / 64, kb = r / nblk, nb = r % nblk, n = nb * 64 + n4;
;         const int sc = n < SRC_GLR ? n : n + GRANK;
;         q.srcp = F.w_in + sc; q.ldw = DIN; q.kscale = F.norm1_w; q.K = D; q.WT = F.Win_t(); q.n0 = nb * 64; q.k0 = kb * 64; return q; }
;     r -= I_IN;
;     if (r < I_OUT) { const int nblk = D / 64, kb = r / nblk, nb = r % nblk;
;         q.srcp = F.w_out + nb * 64 + n4; q.ldw = D; q.kscale = nullptr; q.K = D; q.WT = F.Wout_t(); q.n0 = nb * 64; q.k0 = kb * 64; return q; }
;     r -= I_OUT;
;     if (r < I_GU) { const int nblk = 2 * FF / 64, kb = r / nblk, nb = r % nblk, n0 = nb * 64, pn = n0 >> 8, wc = (n0 >> 6) & 3, bj = n4 >> 5, hl = 32 * wc + (n4 & 31);
;         q.srcp = (bj ? F.w_up : F.w_gate) + pn * 128 + hl; q.ldw = FF; q.kscale = F.norm2_w; q.K = D; q.WT = F.Wgu_t(); q.n0 = n0; q.k0 = kb * 64; return q; }
;     r -= I_GU;
;     { const int nblk = D / 64, kb = r / nblk, nb = r % nblk;
;         q.srcp = F.w_down + nb * 64 + n4; q.ldw = D; q.kscale = nullptr; q.K = FF; q.WT = F.Wdown_t(); q.n0 = nb * 64; q.k0 = kb * 64; return q; }
; __global__ void __launch_bounds__(NTHREADS, 2) hybrid_fwd(Args args) {
;     ...
;                 p1_glr(F, sw, nshort * NWAVES); p0_items<true>(F, P0_NITEMS - P0_DEFER_ITEMS, P0_NITEMS, sw, nshort * NWAVES); }
;             else if ((NT % F.G) == 0) { p1_glr(F, F.vcu * NWAVES + F.wave, F.G * NWAVES); p0_items<true>(F, P0_NITEMS - P0_DEFER_ITEMS, P0_NITEMS, F.vcu * NWAVES + F.wave, F.G * NWAVES); }
.LBB0_399:
	v_lshlrev_b32_e32 v20, 2, v183
	s_add_i32 s35, s0, 0x30b8
	v_and_b32_e32 v142, 60, v20
	s_cmpk_gt_i32 s0, 0x11f7
	v_lshrrev_b32_e32 v143, 4, v183
	s_cbranch_scc1 .LBB0_421
	s_cmpk_gt_i32 s0, 0xecf7
	s_cbranch_scc0 .LBB0_439
	s_cmpk_gt_u32 s35, 0x1cff
	s_cbranch_scc0 .LBB0_912
	s_cmpk_gt_u32 s35, 0x32ff
	s_cbranch_scc0 .LBB0_913
	s_lshl_b32 s0, s35, 6
	s_and_b32 s36, s0, 0x7c0
	s_lshl_b32 s0, s36, 2
	s_add_u32 s0, s94, s0
	s_addc_u32 s1, s95, 0
	s_waitcnt vmcnt(0)
	v_lshlrev_b32_e32 v2, 2, v142
	v_mov_b32_e32 v3, 0
	s_add_u32 s6, s56, 0x1200000
	v_lshl_add_u64 v[18:19], s[0:1], 0, v[2:3]
	s_addc_u32 s7, s57, 0
	s_lshl_b32 s0, s35, 1
	s_and_b32 s0, s0, 0x7fffffc0
	s_add_i32 s37, s0, 0xffff9a00
	s_mov_b64 s[18:19], 0
	s_mov_b64 s[4:5], 0
	s_branch .LBB0_914
